# K tile LDS swizzle widened to 16 rows (row&15) on DMA source and ds_read side: removes 2-way bank conflict of K ds_read_b128
# speedup vs baseline: 1.0039x; 1.0031x over previous
; #define SBAR() __builtin_amdgcn_sched_barrier(0)
; __device__ __forceinline__ int v_rd_base(int lane) { return ((lane & 3) << 3) | (((lane >> 2) & 3) << 6) | (((lane >> 4) & 1) << 5) | (((lane >> 5) & 1) << 8); }
; #define DMAV(t, b) do { DMA1(t, b, 2); DMA1(t, b, 3); } while (0)
; #define LANDED() do { asm volatile("s_waitcnt vmcnt(0)" ::: "memory"); __syncthreads(); } while (0)
; #define BLK_X(N0, N1, P0, P1, alP, t) do { SBAR(); __builtin_amdgcn_s_setprio(1); qkt(N0, N1, KBUF((t) & 3), qr, r32, hi, mapB); \
;     if constexpr (!SH) v_frag_read<0>(vfa, VBUF(((t) - 1) & 3)); \
;     finishSM<SH>(P0, P1, alP, l_reg, pa0, pa1, pa2, pa3); __builtin_amdgcn_s_setprio(0); SBAR(); } while (0)
; template <bool SH> __device__ __forceinline__ void attn_unit(bf16_t* __restrict__ proj, int tok0, int kv0, int seq, int h, float lam, float oscale, const float* __restrict__ subg, char* lds, bool dry) {
;     ...
;   const bf16_t* Qw = proj + (size_t)(tok0 + wq * 32 + r32) * NPROJ + C_Q + h * 128 + mp * 64 + hi * 8;
; #pragma unroll
;   for (int d0 = 0; d0 < 4; ++d0) qr[d0] = *reinterpret_cast<const bf16x8*>(Qw + d0 * 16);
;   unsigned vk0, vv0;
;   { const int c = tid;
;     { const int row = c >> 4, pc = c & 15, scn = pc ^ (row & 7); vk0 = (unsigned)(row * LDK + scn * 8) * 2u; }
;     { const int sub = c >> 5, kk = (sub >> 2) * 8 + ((c >> 2) & 7), col = (sub & 3) * 32 + (c & 3) * 8; vv0 = (unsigned)(kk * LDK + col) * 2u; } }
;   const unsigned ldsb = (unsigned)(uintptr_t)ldsl;
;   const int vbb = (int)(uintptr_t)ldsl + 16384 + v_rd_base(lane);
;     ...
;   DMA(0, 0); LANDED();
;   DMA(1, 1);
;   if (ty == 0) {
;     qkt(pA0, pA1, KBUF(0), qr, r32, hi, mapB); partialSM<SH>(pA0, pA1, m_reg, mnA, alA);
;     LANDED();
;     for (int j = 1; j + 1 < NT; j += 2) {
;       BLK_X(pB0, pB1, pA0, pA1, alA, j); DMAV(j + 1, (j + 1) & 3); BLK_Y(pB0, pB1, mnB, alB, j - 1); LANDED();
;       BLK_X(pA0, pA1, pB0, pB1, alB, j + 1); DMAV(j + 2, (j + 2) & 3); BLK_Y(pA0, pA1, mnA, alA, j); LANDED();
;     }
;     BLK_X(pB0, pB1, pA0, pA1, alA, NT - 1); BLK_Y(pB0, pB1, mnB, alB, NT - 2);
;     finishSM<SH>(pB0, pB1, alB, l_reg, pa0, pa1, pa2, pa3); SBAR();
;     if constexpr (SH) pv_d0(o, VBUF((NT - 1) & 3), pa0, pa1, pa2, pa3); else pv_d0_pipe<false>(o, VBUF((NT - 1) & 3), pa0, pa1, pa2, pa3, vfa);
;   } else {
;     qkt(pA0, pA1, KBUF(0), qr, r32, hi, mapB);
;     LANDED();
.LBB0_353:
	v_mov_b32_e32 v182, v184
	s_mov_b32 s59, s81
	v_readfirstlane_b32 s14, v182
	s_ashr_i32 s17, s14, 6
	s_and_b32 s15, s17, 3
	s_ashr_i32 s16, s14, 8
	s_lshl_b64 s[6:7], s[58:59], 1
	s_add_u32 s8, s68, s6
	s_addc_u32 s9, s69, s7
	s_lshl_b32 s0, s15, 5
	v_and_b32_e32 v205, 31, v182
	s_add_i32 s0, s0, s3
	v_add_u32_e32 v2, s0, v205
	v_mov_b64_e32 v[0:1], s[68:69]
	v_mad_i64_i32 v[0:1], s[0:1], v2, s25, v[0:1]
	s_lshl_b32 s4, s96, 1
	s_mov_b32 s5, s81
	s_lshl_b32 s0, s16, 6
	v_bfe_u32 v204, v182, 5, 1
	v_lshl_add_u64 v[0:1], v[0:1], 0, s[4:5]
	s_ashr_i32 s1, s0, 31
	v_lshl_add_u64 v[0:1], s[0:1], 1, v[0:1]
	v_lshlrev_b32_e32 v252, 4, v204
	v_lshl_add_u64 v[0:1], v[0:1], 0, v[252:253]
	global_load_dwordx4 v[140:143], v[0:1], off offset:3072
	global_load_dwordx4 v[136:139], v[0:1], off offset:3104
	global_load_dwordx4 v[132:135], v[0:1], off offset:3136
	global_load_dwordx4 v[128:131], v[0:1], off offset:3168
	s_add_u32 s20, s8, s4
	s_addc_u32 s21, s9, 0
	s_add_u32 s10, s20, 0x1000
	v_ashrrev_i32_e32 v0, 4, v182
	v_and_b32_e32 v1, 15, v182
	s_addc_u32 s11, s21, 0
	v_bitop3_b32 v1, v0, v1, 15 bitop3:0x6c
	v_mul_lo_u32 v2, v0, s25
	v_ashrrev_i32_e32 v183, 2, v182
	s_add_u32 s8, s20, 0x1400
	v_lshl_or_b32 v166, v1, 4, v2
	v_and_b32_e32 v1, 7, v183
	s_mov_b32 s0, 0x3ffff8
	s_addc_u32 s9, s21, 0
	v_and_or_b32 v0, v0, s0, v1
	v_and_b32_e32 v202, 3, v182
	s_add_i32 s18, 0, 0x4000
	v_and_b32_e32 v1, 0x60, v182
	v_lshlrev_b32_e32 v2, 3, v202
	v_mul_u32_u24_e32 v0, 0xc00, v0
	s_add_u32 s0, s20, 0x31000
	v_and_b32_e32 v203, 63, v182
	v_or3_b32 v0, v2, v1, v0
	v_lshlrev_b32_e32 v1, 4, v182
	s_addc_u32 s1, s21, 0
	v_lshlrev_b32_e32 v207, 1, v0
	v_lshlrev_b32_e32 v0, 3, v203
	v_and_b32_e32 v1, 0xc0, v1
	v_lshlrev_b32_e32 v2, 1, v182
	s_add_u32 s12, s20, 0x31400
	v_and_or_b32 v1, v0, 24, v1
	v_and_b32_e32 v2, 32, v2
	v_and_b32_e32 v0, 0x100, v0
	s_addc_u32 s13, s21, 0
	s_lshl_b32 s17, s17, 10
	v_or3_b32 v206, v1, v2, v0
	s_add_i32 s5, s17, 0
	v_add_u32_e32 v208, s18, v206
	s_add_i32 s19, s5, 0x2000
	s_add_i32 s18, s17, s18
	s_add_i32 s26, s5, 0x6000
	s_mov_b32 s27, m0
	s_mov_b32 m0, s5
	s_nop 0
	global_load_lds_dwordx4 v166, s[10:11]
	s_mov_b32 m0, s19
	s_nop 0
	global_load_lds_dwordx4 v166, s[0:1]
	s_mov_b32 m0, s18
	s_nop 0
	global_load_lds_dwordx4 v207, s[8:9]
	s_mov_b32 m0, s26
	s_nop 0
	global_load_lds_dwordx4 v207, s[12:13]
	s_mov_b32 m0, s27
	s_add_u32 s0, s20, 0x61000
	s_addc_u32 s1, s21, 0
	s_add_u32 s12, s20, 0x61400
	s_addc_u32 s13, s21, 0
	s_add_u32 s18, s20, 0x91000
	s_addc_u32 s19, s21, 0
	s_add_u32 s20, s20, 0x91400
	s_waitcnt vmcnt(0)
	s_barrier
	s_addc_u32 s21, s21, 0
	s_add_i32 s26, s5, 0x8000
	s_add_i32 s27, s5, 0xa000
	s_add_i32 s58, s5, 0xc000
	s_add_i32 s59, s5, 0xe000
	s_mov_b32 s60, m0
	s_mov_b32 m0, s26
	s_nop 0
	global_load_lds_dwordx4 v166, s[0:1]
	s_mov_b32 m0, s27
	s_nop 0
	global_load_lds_dwordx4 v166, s[18:19]
	s_mov_b32 m0, s58
	s_nop 0
	global_load_lds_dwordx4 v207, s[12:13]
	s_mov_b32 m0, s59
	s_nop 0
	global_load_lds_dwordx4 v207, s[20:21]
	s_mov_b32 m0, s60
	s_cmpk_lt_u32 s14, 0x100
	s_cselect_b64 s[0:1], -1, 0
	s_cmpk_gt_u32 s14, 0xff
	s_mov_b64 s[12:13], -1
	v_lshlrev_b32_e32 v209, 8, v205
	v_lshlrev_b32_e32 v210, 4, v205
	s_cbranch_scc0 .LBB0_357
	s_lshl_b32 s12, s16, 7
	v_and_b32_e32 v41, 0xf0, v210
	v_bitop3_b32 v167, s12, v41, v252 bitop3:0x36
	v_add_u32_e32 v165, v167, v209
	v_add_u32_e32 v42, 0, v165
	ds_read_b128 v[0:3], v42
	ds_read_b128 v[16:19], v42 offset:8192
	v_or_b32_e32 v40, s12, v252
	v_bitop3_b32 v168, v40, v41, 32 bitop3:0x36
	s_waitcnt vmcnt(3) lgkmcnt(1)
	v_mfma_f32_32x32x16_bf16 v[0:15], v[0:3], v[140:143], 0
	v_add_u32_e32 v164, v168, v209
	v_add_u32_e32 v43, 0, v164
	ds_read_b128 v[32:35], v43
	ds_read_b128 v[36:39], v43 offset:8192
	v_bitop3_b32 v169, v40, v41, 64 bitop3:0x36
	v_add_u32_e32 v163, v169, v209
	v_add_u32_e32 v44, 0, v163
	s_movk_i32 s12, 0x60
	s_waitcnt lgkmcnt(2)
	v_mfma_f32_32x32x16_bf16 v[16:31], v[16:19], v[140:143], 0
	v_bitop3_b32 v170, v40, v41, s12 bitop3:0x36
	v_add_u32_e32 v162, v170, v209
	v_add_u32_e32 v40, 0, v162
	s_add_u32 s12, s10, 0xc0000
	s_addc_u32 s13, s11, 0
	s_add_u32 s20, s8, 0xc0000
	s_addc_u32 s21, s9, 0
	s_waitcnt vmcnt(2) lgkmcnt(1)
	v_mfma_f32_32x32x16_bf16 v[0:15], v[32:35], v[136:139], v[0:15]
	s_add_u32 s26, s10, 0xf0000
	s_addc_u32 s27, s11, 0
	s_add_u32 s58, s8, 0xf0000
	s_addc_u32 s59, s9, 0
	s_add_i32 s19, s5, 0x10000
	s_add_i32 s60, s5, 0x12000
	s_add_i32 s61, s5, 0x14000
	s_waitcnt lgkmcnt(0)
	v_mfma_f32_32x32x16_bf16 v[16:31], v[36:39], v[136:139], v[16:31]
	ds_read_b128 v[32:35], v44
	ds_read_b128 v[36:39], v44 offset:8192
	s_add_i32 s64, s5, 0x16000
	s_mov_b32 s18, 4
	s_waitcnt vmcnt(1) lgkmcnt(1)
	v_mfma_f32_32x32x16_bf16 v[0:15], v[32:35], v[132:135], v[0:15]
	s_waitcnt lgkmcnt(0)
	v_mfma_f32_32x32x16_bf16 v[16:31], v[36:39], v[132:135], v[16:31]
	ds_read_b128 v[32:35], v40
	ds_read_b128 v[36:39], v40 offset:8192
	s_waitcnt vmcnt(0)
	s_waitcnt lgkmcnt(0)
	s_barrier
; #define PK4(P, BASE, OUT) do { u32x4 w = {cvtpk_b(P[BASE + 0], P[BASE + 1]), cvtpk_b(P[BASE + 2], P[BASE + 3]), cvtpk_b(P[BASE + 4], P[BASE + 5]), cvtpk_b(P[BASE + 6], P[BASE + 7])}; \
;     OUT = *reinterpret_cast<bf16x8*>(&w); } while (0)
; #define LANDED() do { asm volatile("s_waitcnt vmcnt(0)" ::: "memory"); __syncthreads(); } while (0)
; #define BLK_X(N0, N1, P0, P1, alP, t) do { SBAR(); __builtin_amdgcn_s_setprio(1); qkt(N0, N1, KBUF((t) & 3), qr, r32, hi, mapB); \
;     if constexpr (!SH) v_frag_read<0>(vfa, VBUF(((t) - 1) & 3)); \
;     finishSM<SH>(P0, P1, alP, l_reg, pa0, pa1, pa2, pa3); __builtin_amdgcn_s_setprio(0); SBAR(); } while (0)
; template <bool SH> __device__ __forceinline__ void finishSM(f32x16& p0, f32x16& p1, float alpha, float& l_reg, bf16x8& pa0, bf16x8& pa1, bf16x8& pa2, bf16x8& pa3) {
;   if constexpr (!SH) {
; #pragma unroll
;     for (int r = 0; r < 16; ++r) { p0[r] = __builtin_amdgcn_exp2f(p0[r]); p1[r] = __builtin_amdgcn_exp2f(p1[r]); }
;   }
;   float ps = 0;
; #pragma unroll
;   for (int r = 0; r < 16; ++r) ps += p0[r];
; #pragma unroll
;   for (int r = 0; r < 16; ++r) ps += p1[r];
;   if constexpr (SH) l_reg = l_reg * alpha + ps; else l_reg += ps;
;     ...
;   PK4(p0, 0, pa0); PK4(p0, 8, pa1); PK4(p1, 0, pa2); PK4(p1, 8, pa3);
;     ...
; }
; __device__ __forceinline__ void qkt(f32x16& p0, f32x16& p1, const char* Ks, const bf16x8* qr, int r32, int hi, int mapB) {
;   p0 = f32x16{}; p1 = f32x16{};
; #pragma unroll
;   for (int d0 = 0; d0 < 4; ++d0) { const int cb = (d0 * 16 + hi * 8) * 2 + mapB;
;     bf16x8 b0 = *reinterpret_cast<const bf16x8*>(Ks + KSWZ(r32, cb));
;     bf16x8 b1 = *reinterpret_cast<const bf16x8*>(Ks + KSWZ(32 + r32, cb));
;     p0 = __builtin_amdgcn_mfma_f32_32x32x16_bf16(b0, qr[d0], p0, 0, 0, 0);
;     p1 = __builtin_amdgcn_mfma_f32_32x32x16_bf16(b1, qr[d0], p1, 0, 0, 0); }
; }
; template <bool SH> __device__ __forceinline__ void attn_unit(bf16_t* __restrict__ proj, int tok0, int kv0, int seq, int h, float lam, float oscale, const float* __restrict__ subg, char* lds, bool dry) {
;     ...
;     DMA(2, 2); DMA1X(2, 2, 0, wid - 4); DMA1X(2, 2, 1, wid - 4); partialSM<SH>(pA0, pA1, m_reg, mnA, alA); BLK_X(pB0, pB1, pA0, pA1, alA, 1); LANDED();
	s_mov_b32 s65, m0
	s_mov_b32 m0, s19
	s_nop 0
	global_load_lds_dwordx4 v166, s[12:13]
	s_mov_b32 m0, s60
	s_nop 0
	global_load_lds_dwordx4 v166, s[26:27]
	s_mov_b32 m0, s61
	s_nop 0
	global_load_lds_dwordx4 v207, s[20:21]
	s_mov_b32 m0, s64
	s_nop 0
	global_load_lds_dwordx4 v207, s[58:59]
	s_mov_b32 m0, s65
	s_add_u32 s12, s10, 0xa8000
	s_waitcnt vmcnt(0)
	v_mfma_f32_32x32x16_bf16 v[0:15], v[32:35], v[128:131], v[0:15]
	s_addc_u32 s13, s11, 0
	s_add_i32 s19, s17, 0xfffff000
	s_add_i32 s20, s5, 0xf000
	s_setprio 3
	s_mov_b32 s21, m0
	s_mov_b32 m0, s20
	s_nop 0
	global_load_lds_dwordx4 v166, s[12:13]
	s_mov_b32 m0, s21
	s_setprio 0
	s_add_u32 s12, s10, 0xd8000
	s_addc_u32 s13, s11, 0
	s_add_i32 s20, s5, 0x11000
	v_mfma_f32_32x32x16_bf16 v[16:31], v[36:39], v[128:131], v[16:31]
	s_setprio 3
	s_mov_b32 s21, m0
	s_mov_b32 m0, s20
	s_nop 0
	global_load_lds_dwordx4 v166, s[12:13]
	s_mov_b32 m0, s21
	s_setprio 0
	s_setprio 1
	ds_read_b128 v[32:35], v42 offset:32768
	ds_read_b128 v[36:39], v42 offset:40960
	s_waitcnt lgkmcnt(1)
	v_mfma_f32_32x32x16_bf16 v[64:79], v[32:35], v[140:143], 0
	s_waitcnt lgkmcnt(0)
	v_mfma_f32_32x32x16_bf16 v[80:95], v[36:39], v[140:143], 0
	ds_read_b128 v[32:35], v43 offset:32768
	ds_read_b128 v[36:39], v43 offset:40960
	s_waitcnt lgkmcnt(1)
	v_mfma_f32_32x32x16_bf16 v[64:79], v[32:35], v[136:139], v[64:79]
	s_waitcnt lgkmcnt(0)
	v_mfma_f32_32x32x16_bf16 v[80:95], v[36:39], v[136:139], v[80:95]
	ds_read_b128 v[32:35], v44 offset:32768
	ds_read_b128 v[36:39], v44 offset:40960
	s_waitcnt lgkmcnt(1)
	v_mfma_f32_32x32x16_bf16 v[64:79], v[32:35], v[132:135], v[64:79]
	s_waitcnt lgkmcnt(0)
	v_mfma_f32_32x32x16_bf16 v[80:95], v[36:39], v[132:135], v[80:95]
	ds_read_b128 v[32:35], v40 offset:32768
	ds_read_b128 v[36:39], v40 offset:40960
	ds_read_b64_tr_b16 v[156:157], v208 offset:0
	ds_read_b64_tr_b16 v[158:159], v208 offset:0x800
	ds_read_b64_tr_b16 v[152:153], v208 offset:0x1000
	ds_read_b64_tr_b16 v[154:155], v208 offset:0x1800
	ds_read_b64_tr_b16 v[148:149], v208 offset:0x2000
	ds_read_b64_tr_b16 v[150:151], v208 offset:0x2800
	s_waitcnt lgkmcnt(1)
	v_mfma_f32_32x32x16_bf16 v[64:79], v[32:35], v[128:131], v[64:79]
	ds_read_b64_tr_b16 v[144:145], v208 offset:0x3000
	ds_read_b64_tr_b16 v[146:147], v208 offset:0x3800
	s_waitcnt lgkmcnt(0)
	v_mfma_f32_32x32x16_bf16 v[80:95], v[36:39], v[128:131], v[80:95]
	s_setprio 0
	v_exp_f32_e32 v0, v0
	v_exp_f32_e32 v1, v1
	v_exp_f32_e32 v2, v2
	v_exp_f32_e32 v3, v3
	v_exp_f32_e32 v4, v4
	v_add_f32_e32 v32, 0, v0
	v_exp_f32_e32 v5, v5
	v_add_f32_e32 v32, v1, v32
	v_exp_f32_e32 v6, v6
	v_add_f32_e32 v32, v2, v32
	v_exp_f32_e32 v7, v7
	v_add_f32_e32 v32, v3, v32
	v_exp_f32_e32 v8, v8
	v_add_f32_e32 v32, v4, v32
	v_exp_f32_e32 v9, v9
	v_add_f32_e32 v32, v5, v32
	v_exp_f32_e32 v10, v10
	v_add_f32_e32 v32, v6, v32
	v_exp_f32_e32 v11, v11
	v_add_f32_e32 v32, v7, v32
	v_exp_f32_e32 v12, v12
	v_add_f32_e32 v32, v8, v32
	v_exp_f32_e32 v13, v13
	v_add_f32_e32 v32, v9, v32
	v_exp_f32_e32 v14, v14
	v_add_f32_e32 v32, v10, v32
	v_exp_f32_e32 v15, v15
	v_add_f32_e32 v32, v11, v32
	v_exp_f32_e32 v16, v16
	v_add_f32_e32 v32, v12, v32
	v_exp_f32_e32 v17, v17
	v_add_f32_e32 v32, v13, v32
	v_exp_f32_e32 v18, v18
	v_add_f32_e32 v32, v14, v32
	v_exp_f32_e32 v19, v19
	v_add_f32_e32 v32, v15, v32
	v_exp_f32_e32 v20, v20
	v_add_f32_e32 v32, v16, v32
	v_exp_f32_e32 v21, v21
	v_add_f32_e32 v32, v17, v32
	v_exp_f32_e32 v22, v22
	v_add_f32_e32 v32, v18, v32
	v_exp_f32_e32 v23, v23
	v_add_f32_e32 v32, v19, v32
	v_exp_f32_e32 v24, v24
	v_add_f32_e32 v32, v20, v32
	v_exp_f32_e32 v25, v25
	v_add_f32_e32 v32, v21, v32
	v_exp_f32_e32 v26, v26
	v_add_f32_e32 v32, v22, v32
	v_exp_f32_e32 v27, v27
	v_add_f32_e32 v32, v23, v32
	v_exp_f32_e32 v28, v28
	v_add_f32_e32 v32, v24, v32
	v_exp_f32_e32 v29, v29
	v_add_f32_e32 v32, v25, v32
	v_exp_f32_e32 v30, v30
	v_add_f32_e32 v32, v26, v32
	v_exp_f32_e32 v31, v31
	v_add_f32_e32 v32, v27, v32
	v_add_f32_e32 v32, v28, v32
	v_add_f32_e32 v32, v29, v32
	s_add_u32 s12, s80, s6
	s_waitcnt vmcnt(0)
	v_add_f32_e32 v32, v30, v32
	s_addc_u32 s13, 0, s7
	v_readlane_b32 s20, v255, 6
	v_add_f32_e32 v32, v31, v32
	s_add_u32 s12, s20, s12
	v_readlane_b32 s20, v255, 8
	v_mov_b32_e32 v48, 0
	v_add_f32_e32 v171, 0, v32
	v_cvt_pk_bf16_f32 v108, v0, v1
	v_cvt_pk_bf16_f32 v109, v2, v3
	v_cvt_pk_bf16_f32 v110, v4, v5
	v_cvt_pk_bf16_f32 v111, v6, v7
	v_cvt_pk_bf16_f32 v104, v8, v9
	v_cvt_pk_bf16_f32 v105, v10, v11
	v_cvt_pk_bf16_f32 v106, v12, v13
	v_cvt_pk_bf16_f32 v107, v14, v15
	v_cvt_pk_bf16_f32 v100, v16, v17
	v_cvt_pk_bf16_f32 v101, v18, v19
	v_cvt_pk_bf16_f32 v102, v20, v21
	v_cvt_pk_bf16_f32 v103, v22, v23
	v_cvt_pk_bf16_f32 v96, v24, v25
	v_cvt_pk_bf16_f32 v97, v26, v27
	v_cvt_pk_bf16_f32 v98, v28, v29
	v_cvt_pk_bf16_f32 v99, v30, v31
	s_addc_u32 s13, s20, s13
	s_mov_b32 s20, 0x18000
	v_mov_b32_e32 v49, v48
	v_mov_b32_e32 v50, v48
	v_mov_b32_e32 v51, v48
	v_mov_b32_e32 v52, v48
	v_mov_b32_e32 v53, v48
	v_mov_b32_e32 v54, v48
	v_mov_b32_e32 v55, v48
	v_mov_b32_e32 v56, v48
	v_mov_b32_e32 v57, v48
	v_mov_b32_e32 v58, v48
	v_mov_b32_e32 v59, v48
	v_mov_b32_e32 v60, v48
	v_mov_b32_e32 v61, v48
	v_mov_b32_e32 v62, v48
	v_mov_b32_e32 v63, v48
	v_mov_b32_e32 v32, v48
	v_mov_b32_e32 v33, v48
	v_mov_b32_e32 v34, v48
	v_mov_b32_e32 v35, v48
	v_mov_b32_e32 v36, v48
	v_mov_b32_e32 v37, v48
	v_mov_b32_e32 v38, v48
	v_mov_b32_e32 v39, v48
	v_mov_b32_e32 v40, v48
	v_mov_b32_e32 v41, v48
	v_mov_b32_e32 v42, v48
	v_mov_b32_e32 v43, v48
	v_mov_b32_e32 v44, v48
	v_mov_b32_e32 v45, v48
	v_mov_b32_e32 v46, v48
	v_mov_b32_e32 v47, v48
	v_mov_b32_e32 v16, v48
	v_mov_b32_e32 v17, v48
	v_mov_b32_e32 v18, v48
	v_mov_b32_e32 v19, v48
	v_mov_b32_e32 v20, v48
	v_mov_b32_e32 v21, v48
	v_mov_b32_e32 v22, v48
	v_mov_b32_e32 v23, v48
	v_mov_b32_e32 v24, v48
	v_mov_b32_e32 v25, v48
	v_mov_b32_e32 v26, v48
	v_mov_b32_e32 v27, v48
	v_mov_b32_e32 v28, v48
	v_mov_b32_e32 v29, v48
	v_mov_b32_e32 v30, v48
	v_mov_b32_e32 v31, v48
	v_mov_b32_e32 v0, v48
	v_mov_b32_e32 v1, v48
	v_mov_b32_e32 v2, v48
	v_mov_b32_e32 v3, v48
	v_mov_b32_e32 v4, v48
	v_mov_b32_e32 v5, v48
	v_mov_b32_e32 v6, v48
	v_mov_b32_e32 v7, v48
	v_mov_b32_e32 v8, v48
	v_mov_b32_e32 v9, v48
	v_mov_b32_e32 v10, v48
	v_mov_b32_e32 v11, v48
	v_mov_b32_e32 v12, v48
	v_mov_b32_e32 v13, v48
	v_mov_b32_e32 v14, v48
	v_mov_b32_e32 v15, v48
	s_barrier

; #define LANDED() do { asm volatile("s_waitcnt vmcnt(0)" ::: "memory"); __syncthreads(); } while (0)
; __device__ __forceinline__ void qkt(f32x16& p0, f32x16& p1, const char* Ks, const bf16x8* qr, int r32, int hi, int mapB) {
;   p0 = f32x16{}; p1 = f32x16{};
; #pragma unroll
;   for (int d0 = 0; d0 < 4; ++d0) { const int cb = (d0 * 16 + hi * 8) * 2 + mapB;
;     bf16x8 b0 = *reinterpret_cast<const bf16x8*>(Ks + KSWZ(r32, cb));
;     bf16x8 b1 = *reinterpret_cast<const bf16x8*>(Ks + KSWZ(32 + r32, cb));
;     p0 = __builtin_amdgcn_mfma_f32_32x32x16_bf16(b0, qr[d0], p0, 0, 0, 0);
;     p1 = __builtin_amdgcn_mfma_f32_32x32x16_bf16(b1, qr[d0], p1, 0, 0, 0); }
; }
; template <bool SH> __device__ __forceinline__ void attn_unit(bf16_t* __restrict__ proj, int tok0, int kv0, int seq, int h, float lam, float oscale, const float* __restrict__ subg, char* lds, bool dry) {
;     ...
;   if (ty == 0) {
;     qkt(pA0, pA1, KBUF(0), qr, r32, hi, mapB); partialSM<SH>(pA0, pA1, m_reg, mnA, alA);
;     LANDED();
.LBB0_357:
	s_and_b64 vcc, exec, s[12:13]
	s_cbranch_vccz .LBB0_361
	s_nop 4
	v_and_b32_e32 v16, 0xf0, v210
	v_bitop3_b32 v148, v252, v209, v16 bitop3:0xde
	s_nop 2
	v_add_u32_e32 v4, 0, v148
	ds_read_b128 v[0:3], v4
	ds_read_b128 v[4:7], v4 offset:8192
	v_or_b32_e32 v12, 64, v252
	v_bitop3_b32 v146, v12, v209, v16 bitop3:0xde
	v_add_u32_e32 v12, 0, v146
	s_movk_i32 s8, 0xf0
	v_or_b32_e32 v17, 0x60, v252
	v_bitop3_b32 v149, v252, v210, s8 bitop3:0x78
	s_movk_i32 s8, 0x60
	s_waitcnt vmcnt(3) lgkmcnt(1)
	v_mfma_f32_32x32x16_bf16 v[64:79], v[0:3], v[140:143], 0
	v_or_b32_e32 v0, 32, v252
	v_bitop3_b32 v147, v0, v209, v16 bitop3:0xde
	v_add_u32_e32 v8, 0, v147
	ds_read_b128 v[0:3], v8
	ds_read_b128 v[8:11], v8 offset:8192
	v_bitop3_b32 v145, v17, v209, v16 bitop3:0xde
	v_bitop3_b32 v150, v252, v16, 32 bitop3:0x36
	v_bitop3_b32 v151, v252, v16, 64 bitop3:0x36
	s_waitcnt lgkmcnt(2)
	v_mfma_f32_32x32x16_bf16 v[80:95], v[4:7], v[140:143], 0
	ds_read_b128 v[4:7], v12
	ds_read_b128 v[12:15], v12 offset:8192
	v_bitop3_b32 v152, v252, v16, s8 bitop3:0x36
	v_add_u32_e32 v16, 0, v145
	s_add_u32 s6, s80, s6
	s_addc_u32 s7, 0, s7
	v_readlane_b32 s8, v255, 10
	s_add_u32 s6, s8, s6
	s_waitcnt vmcnt(2) lgkmcnt(3)
	v_mfma_f32_32x32x16_bf16 v[64:79], v[0:3], v[136:139], v[64:79]
	ds_read_b128 v[0:3], v16
	ds_read_b128 v[16:19], v16 offset:8192
	s_waitcnt vmcnt(0)
	v_readlane_b32 s8, v255, 12
	v_mov_b32_e32 v144, 0
	s_addc_u32 s7, s8, s7
	s_mov_b32 s9, 0x10000
	s_mov_b32 s8, 2
	s_waitcnt lgkmcnt(4)
	v_mfma_f32_32x32x16_bf16 v[80:95], v[8:11], v[136:139], v[80:95]
	v_mov_b32_e32 v48, 0
	v_mov_b32_e32 v49, v144
	v_mov_b32_e32 v50, v144
	v_mov_b32_e32 v51, v144
	v_mov_b32_e32 v52, v144
	v_mov_b32_e32 v53, v144
	v_mov_b32_e32 v54, v144
	s_waitcnt vmcnt(1) lgkmcnt(3)
	v_mfma_f32_32x32x16_bf16 v[64:79], v[4:7], v[132:135], v[64:79]
	v_mov_b32_e32 v55, v144
	v_mov_b32_e32 v56, v144
	v_mov_b32_e32 v57, v144
	v_mov_b32_e32 v58, v144
	v_mov_b32_e32 v59, v144
	v_mov_b32_e32 v60, v144
	v_mov_b32_e32 v61, v144
	s_waitcnt lgkmcnt(2)
	v_mfma_f32_32x32x16_bf16 v[80:95], v[12:15], v[132:135], v[80:95]
	v_mov_b32_e32 v62, v144
	v_mov_b32_e32 v63, v144
	v_mov_b32_e32 v32, 0
	v_mov_b32_e32 v33, v144
	v_mov_b32_e32 v34, v144
	v_mov_b32_e32 v35, v144
	v_mov_b32_e32 v36, v144
	s_waitcnt vmcnt(0) lgkmcnt(1)
	v_mfma_f32_32x32x16_bf16 v[64:79], v[0:3], v[128:131], v[64:79]
	v_mov_b32_e32 v37, v144
	v_mov_b32_e32 v38, v144
	v_mov_b32_e32 v39, v144
	v_mov_b32_e32 v40, v144
	v_mov_b32_e32 v41, v144
	v_mov_b32_e32 v42, v144
	v_mov_b32_e32 v43, v144
	s_waitcnt lgkmcnt(0)
	v_mfma_f32_32x32x16_bf16 v[80:95], v[16:19], v[128:131], v[80:95]
	v_mov_b32_e32 v44, v144
	v_mov_b32_e32 v45, v144
	v_mov_b32_e32 v46, v144
	v_mov_b32_e32 v47, v144
	v_mov_b32_e32 v16, 0
	v_mov_b32_e32 v17, v144
	v_mov_b32_e32 v18, v144
	v_mov_b32_e32 v19, v144
	v_mov_b32_e32 v20, v144
	v_mov_b32_e32 v21, v144
	v_mov_b32_e32 v22, v144
	v_mov_b32_e32 v23, v144
	v_mov_b32_e32 v24, v144
	v_mov_b32_e32 v25, v144
	v_mov_b32_e32 v26, v144
	v_mov_b32_e32 v27, v144
	v_mov_b32_e32 v28, v144
	v_mov_b32_e32 v29, v144
	v_mov_b32_e32 v30, v144
	v_mov_b32_e32 v31, v144
	v_mov_b32_e32 v0, 0
	v_mov_b32_e32 v1, v144
	v_mov_b32_e32 v2, v144
	v_mov_b32_e32 v3, v144
	v_mov_b32_e32 v4, v144
	v_mov_b32_e32 v5, v144
	v_mov_b32_e32 v6, v144
	v_mov_b32_e32 v7, v144
	v_mov_b32_e32 v8, v144
	v_mov_b32_e32 v9, v144
	v_mov_b32_e32 v10, v144
	v_mov_b32_e32 v11, v144
	v_mov_b32_e32 v12, v144
	v_mov_b32_e32 v13, v144
	v_mov_b32_e32 v14, v144
	v_mov_b32_e32 v15, v144
	s_barrier
